# grid barrier one-level release; XCD leader no longer bumps (and waits on) the unused per-XCD generation word
# speedup vs baseline: 1.0032x; 1.0032x over previous
.LBB0_251:
	s_or_b64 exec, exec, s[12:13]
	s_mov_b64 s[12:13], exec
	v_mbcnt_lo_u32_b32 v0, s12, 0
	v_mbcnt_hi_u32_b32 v0, s13, v0
	v_cmp_eq_u32_e32 vcc, 0, v0
	s_waitcnt vmcnt(0)
	buffer_inv sc1
	s_and_saveexec_b64 s[14:15], vcc
	s_cbranch_execz .LBB0_253
	s_bcnt1_i32_b64 s12, s[12:13]
.LBB0_253:
	s_or_b64 exec, exec, s[14:15]
	s_waitcnt vmcnt(0)

.LBB0_264:
	s_ashr_i32 s55, s54, 31
	s_lshl_b64 s[56:57], s[54:55], 20
	s_add_u32 s56, s10, s56
	s_addc_u32 s57, s11, s57
	s_and_b64 s[58:59], s[4:5], exec
	s_cselect_b32 s55, s57, s63
	s_cselect_b32 s61, s56, s62
	s_ashr_i32 s51, s50, 31
	s_lshl_b64 s[58:59], s[50:51], 20
	s_add_u32 s58, s46, s58
	s_addc_u32 s59, s47, s59
	s_and_b64 s[66:67], s[4:5], exec
	s_cselect_b32 s51, s59, s65
	s_cselect_b32 s68, s58, s64
	s_add_u32 s62, s62, 0x80080
	s_addc_u32 s63, s63, 0
	s_add_u32 s69, s64, 0x100
	v_mov_b32_e32 v0, 0
	s_addc_u32 s94, s65, 0
	s_mov_b32 s95, -2
	v_mov_b32_e32 v1, v0
	v_mov_b32_e32 v2, v0
	v_mov_b32_e32 v3, v0
	v_mov_b32_e32 v4, v0
	v_mov_b32_e32 v5, v0
	v_mov_b32_e32 v6, v0
	v_mov_b32_e32 v7, v0
	s_waitcnt vmcnt(0)
	v_mov_b32_e32 v16, v0
	v_mov_b32_e32 v17, v0
	v_mov_b32_e32 v18, v0
	v_mov_b32_e32 v19, v0
	v_mov_b32_e32 v20, v0
	v_mov_b32_e32 v21, v0
	v_mov_b32_e32 v22, v0
	v_mov_b32_e32 v23, v0
	v_mov_b32_e32 v32, v0
	v_mov_b32_e32 v33, v0
	v_mov_b32_e32 v34, v0
	v_mov_b32_e32 v35, v0
	v_mov_b32_e32 v36, v0
	v_mov_b32_e32 v37, v0
	v_mov_b32_e32 v38, v0
	v_mov_b32_e32 v39, v0
	v_mov_b32_e32 v48, v0
	v_mov_b32_e32 v49, v0
	v_mov_b32_e32 v50, v0
	v_mov_b32_e32 v51, v0
	v_mov_b32_e32 v52, v0
	v_mov_b32_e32 v53, v0
	v_mov_b32_e32 v54, v0
	v_mov_b32_e32 v55, v0
	v_mov_b32_e32 v8, v0
	v_mov_b32_e32 v9, v0
	v_mov_b32_e32 v10, v0
	v_mov_b32_e32 v11, v0
	v_mov_b32_e32 v12, v0
	v_mov_b32_e32 v13, v0
	v_mov_b32_e32 v14, v0
	v_mov_b32_e32 v15, v0
	v_mov_b32_e32 v24, v0
	v_mov_b32_e32 v25, v0
	v_mov_b32_e32 v26, v0
	v_mov_b32_e32 v27, v0
	v_mov_b32_e32 v28, v0
	v_mov_b32_e32 v29, v0
	v_mov_b32_e32 v30, v0
	v_mov_b32_e32 v31, v0
	v_mov_b32_e32 v40, v0
	v_mov_b32_e32 v41, v0
	v_mov_b32_e32 v42, v0
	v_mov_b32_e32 v43, v0
	v_mov_b32_e32 v44, v0
	v_mov_b32_e32 v45, v0
	v_mov_b32_e32 v46, v0
	v_mov_b32_e32 v47, v0
	v_mov_b32_e32 v56, v0
	v_mov_b32_e32 v57, v0
	v_mov_b32_e32 v58, v0
	v_mov_b32_e32 v59, v0
	v_mov_b32_e32 v60, v0
	v_mov_b32_e32 v61, v0
	v_mov_b32_e32 v62, v0
	v_mov_b32_e32 v63, v0
	v_mov_b32_e32 v64, v0
	v_mov_b32_e32 v65, v0
	v_mov_b32_e32 v66, v0
	v_mov_b32_e32 v67, v0
	v_mov_b32_e32 v68, v0
	v_mov_b32_e32 v69, v0
	v_mov_b32_e32 v70, v0
	v_mov_b32_e32 v71, v0
	v_mov_b32_e32 v80, v0
	v_mov_b32_e32 v81, v0
	v_mov_b32_e32 v82, v0
	v_mov_b32_e32 v83, v0
	v_mov_b32_e32 v84, v0
	v_mov_b32_e32 v85, v0
	v_mov_b32_e32 v86, v0
	v_mov_b32_e32 v87, v0
	v_mov_b32_e32 v96, v0
	v_mov_b32_e32 v97, v0
	v_mov_b32_e32 v98, v0
	v_mov_b32_e32 v99, v0
	v_mov_b32_e32 v100, v0
	v_mov_b32_e32 v101, v0
	v_mov_b32_e32 v102, v0
	v_mov_b32_e32 v103, v0
	v_mov_b32_e32 v112, v0
	v_mov_b32_e32 v113, v0
	v_mov_b32_e32 v114, v0
	v_mov_b32_e32 v115, v0
	v_mov_b32_e32 v116, v0
	v_mov_b32_e32 v117, v0
	v_mov_b32_e32 v118, v0
	v_mov_b32_e32 v119, v0
	v_mov_b32_e32 v72, v0
	v_mov_b32_e32 v73, v0
	v_mov_b32_e32 v74, v0
	v_mov_b32_e32 v75, v0
	v_mov_b32_e32 v76, v0
	v_mov_b32_e32 v77, v0
	v_mov_b32_e32 v78, v0
	v_mov_b32_e32 v79, v0
	v_mov_b32_e32 v88, v0
	v_mov_b32_e32 v89, v0
	v_mov_b32_e32 v90, v0
	v_mov_b32_e32 v91, v0
	v_mov_b32_e32 v92, v0
	v_mov_b32_e32 v93, v0
	v_mov_b32_e32 v94, v0
	v_mov_b32_e32 v95, v0
	v_mov_b32_e32 v104, v0
	v_mov_b32_e32 v105, v0
	v_mov_b32_e32 v106, v0
	v_mov_b32_e32 v107, v0
	v_mov_b32_e32 v108, v0
	v_mov_b32_e32 v109, v0
	v_mov_b32_e32 v110, v0
	v_mov_b32_e32 v111, v0
	v_mov_b32_e32 v120, v0
	v_mov_b32_e32 v121, v0
	v_mov_b32_e32 v122, v0
	v_mov_b32_e32 v123, v0
	v_mov_b32_e32 v124, v0
	v_mov_b32_e32 v125, v0
	v_mov_b32_e32 v126, v0
	v_mov_b32_e32 v127, v0
	s_nop 0
	s_nop 0
	s_nop 0
	s_nop 0

.LBB0_545:
	s_or_b64 exec, exec, s[38:39]
	s_mov_b64 s[38:39], exec
	v_mbcnt_lo_u32_b32 v0, s38, 0
	v_mbcnt_hi_u32_b32 v0, s39, v0
	v_cmp_eq_u32_e32 vcc, 0, v0
	s_waitcnt vmcnt(0)
	buffer_inv sc1
	s_and_saveexec_b64 s[40:41], vcc
	s_cbranch_execz .LBB0_547
	s_bcnt1_i32_b64 s38, s[38:39]
.LBB0_547:
	s_or_b64 exec, exec, s[40:41]
	s_waitcnt vmcnt(0)

.LBB0_553:
	s_or_b32 s4, s63, s60
	v_mov_b32_e32 v233, v225
	s_bitcmp0_b32 s63, 0
	s_cselect_b32 s70, s59, s61
	v_readfirstlane_b32 s68, v233
	s_bfe_u32 s65, s68, 0x20006
	s_lshl_b32 s71, s70, 7
	s_lshl_b32 s67, s65, 5
	v_and_b32_e32 v231, 31, v233
	s_or_b32 s69, s67, s71
	s_add_i32 s40, s4, s62
	v_or_b32_e32 v212, s69, v231
	s_ashr_i32 s41, s40, 31
	s_ashr_i32 s66, s68, 8
	s_lshl_b64 s[42:43], s[40:41], 19
	v_lshl_add_u64 v[0:1], s[38:39], 0, v[212:213]
	s_add_u32 s72, s14, s42
	v_mad_u64_u32 v[2:3], s[40:41], v0, s44, v[214:215]
	s_addc_u32 s73, s15, s43
	v_mad_i32_i24 v3, v1, s44, v3
	s_lshl_b32 s64, s4, 7
	s_lshl_b32 s4, s4, 8
	s_lshl_b32 s40, s66, 6
	v_bfe_u32 v4, v233, 5, 1
	v_lshl_add_u64 v[0:1], v[2:3], 0, s[4:5]
	s_ashr_i32 s41, s40, 31
	v_lshl_add_u64 v[0:1], s[40:41], 1, v[0:1]
	v_lshlrev_b32_e32 v216, 4, v4
	v_mov_b32_e32 v217, v213
	v_lshl_add_u64 v[0:1], v[0:1], 0, v[216:217]
	v_lshl_add_u64 v[2:3], v[0:1], 0, s[6:7]
	v_add_co_u32_e32 v0, vcc, s45, v0
	s_add_u32 s42, s81, s42
	s_nop 0
	v_addc_co_u32_e32 v1, vcc, 0, v1, vcc
	global_load_dwordx4 v[128:131], v[2:3], off offset:32
	global_load_dwordx4 v[132:135], v[2:3], off offset:64
	global_load_dwordx4 v[136:139], v[0:1], off offset:2048
	global_load_dwordx4 v[140:143], v[2:3], off offset:96
	v_lshlrev_b32_e32 v0, 3, v233
	s_addc_u32 s43, s82, s43
	v_ashrrev_i32_e32 v1, 31, v0
	s_lshl_b32 s41, s70, 1
	v_lshlrev_b64 v[0:1], 1, v[0:1]
	v_mov_b32_e32 v246, v0
	v_add_u32_e32 v245, 0x2000, v0
	s_or_b32 s70, s41, 1
	s_mov_b64 s[88:89], s[72:73]
	v_lshl_add_u64 v[218:219], s[72:73], 0, v[0:1]
	s_lshl_b32 s4, s70, 14
	s_mov_b64 s[90:91], s[42:43]
	v_lshl_add_u64 v[220:221], s[42:43], 0, v[0:1]
	v_lshl_add_u64 v[0:1], v[218:219], 0, s[4:5]
	s_barrier
	v_lshl_add_u64 v[2:3], v[220:221], 0, s[4:5]
	global_load_dwordx4 v[144:147], v[0:1], off
	global_load_dwordx4 v[148:151], v[2:3], off
	v_add_co_u32_e32 v0, vcc, s47, v0
	v_lshlrev_b32_e32 v217, 3, v4
	s_nop 0
	v_addc_co_u32_e32 v1, vcc, 0, v1, vcc
	v_add_co_u32_e32 v2, vcc, s47, v2
	v_mul_u32_u24_e32 v230, 0x110, v231
	s_nop 0
	v_addc_co_u32_e32 v3, vcc, 0, v3, vcc
	global_load_dwordx4 v[152:155], v[0:1], off
	global_load_dwordx4 v[156:159], v[2:3], off
	v_lshrrev_b32_e32 v0, 4, v233
	v_lshlrev_b32_e32 v2, 4, v233
	v_mov_b32_e32 v1, 0x14e60
	v_lshrrev_b32_e32 v3, 3, v233
	v_mul_lo_u32 v5, v0, s46
	v_and_b32_e32 v0, 0x70, v2
	v_and_b32_e32 v6, 0xf0, v2
	v_mad_u64_u32 v[222:223], s[42:43], v3, s48, v[0:1]
	v_add3_u32 v234, 0, v5, v6
	v_add_u32_e32 v0, 0, v222
	v_or_b32_e32 v2, s40, v217
	v_lshlrev_b32_e32 v2, 1, v2
	v_mov_b32_e32 v48, v213
	v_mov_b32_e32 v49, v213
	v_mov_b32_e32 v62, v213
	v_mov_b32_e32 v63, v213
	v_lshlrev_b32_e32 v232, 2, v4
	v_add3_u32 v235, 0, v230, v2
	v_mad_u32_u24 v236, v231, s48, v1
	v_mov_b32_e32 v50, v213
	v_mov_b32_e32 v51, v213
	v_mov_b32_e32 v52, v213
	v_mov_b32_e32 v53, v213
	v_mov_b32_e32 v54, v213
	v_mov_b32_e32 v55, v213
	v_mov_b32_e32 v56, v213
	v_mov_b32_e32 v57, v213
	v_mov_b32_e32 v58, v213
	v_mov_b32_e32 v59, v213
	v_mov_b32_e32 v60, v213
	v_mov_b32_e32 v61, v213
	v_mov_b64_e32 v[32:33], v[48:49]
	v_mov_b64_e32 v[16:17], v[48:49]
	s_waitcnt vmcnt(8)
	v_mov_b64_e32 v[78:79], v[62:63]
	s_mov_b32 s72, 1
	s_waitcnt vmcnt(3)
	ds_write_b128 v234, v[144:147]
	s_waitcnt vmcnt(2)
	ds_write_b128 v0, v[148:151] offset:34816
	s_waitcnt vmcnt(1)
	ds_write_b128 v234, v[152:155] offset:8704
	s_waitcnt vmcnt(0)
	ds_write_b128 v0, v[156:159] offset:44032
	v_mov_b32_e32 v0, 0x14e40
	v_mad_u32_u24 v237, v231, s48, v0
	v_mov_b32_e32 v0, 0x14e20
	v_mad_u32_u24 v238, v231, s48, v0
	v_mov_b32_e32 v0, 0x14e00
	v_mad_u32_u24 v239, v231, s48, v0
	v_mov_b32_e32 v0, 0x13c00
	v_mad_u32_u24 v240, v231, s48, v0
	v_mov_b32_e32 v0, 0x12a60
	v_mad_u32_u24 v241, v231, s48, v0
	v_mov_b32_e32 v0, 0x12a40
	v_mad_u32_u24 v242, v231, s48, v0
	v_mov_b32_e32 v0, 0x12a20
	v_mad_u32_u24 v243, v231, s48, v0
	v_mov_b32_e32 v0, 0x12a00
	v_mad_u32_u24 v244, v231, s48, v0
	v_mov_b32_e32 v0, 0x11800
	v_mad_u32_u24 v248, v231, s48, v0
	v_add_u32_e32 v248, v248, v216
	v_mov_b64_e32 v[0:1], v[48:49]
	s_mov_b32 s73, 0
	s_mov_b32 s74, 2
	s_or_b32 s75, s69, 31
	s_mov_b64 s[42:43], 0
	v_mov_b32_e32 v224, 1.0
	v_mov_b32_e32 v249, 0xf149f2ca
	v_mov_b32_e32 v223, 0
	s_mov_b32 s4, s41
	v_mov_b64_e32 v[34:35], v[50:51]
	v_mov_b64_e32 v[36:37], v[52:53]
	v_mov_b64_e32 v[38:39], v[54:55]
	v_mov_b64_e32 v[40:41], v[56:57]
	v_mov_b64_e32 v[42:43], v[58:59]
	v_mov_b64_e32 v[44:45], v[60:61]
	v_mov_b64_e32 v[46:47], v[62:63]
	v_mov_b64_e32 v[18:19], v[50:51]
	v_mov_b64_e32 v[20:21], v[52:53]
	v_mov_b64_e32 v[22:23], v[54:55]
	v_mov_b64_e32 v[24:25], v[56:57]
	v_mov_b64_e32 v[26:27], v[58:59]
	v_mov_b64_e32 v[28:29], v[60:61]
	v_mov_b64_e32 v[30:31], v[62:63]
	v_mov_b64_e32 v[2:3], v[50:51]
	v_mov_b64_e32 v[4:5], v[52:53]
	v_mov_b64_e32 v[6:7], v[54:55]
	v_mov_b64_e32 v[8:9], v[56:57]
	v_mov_b64_e32 v[10:11], v[58:59]
	v_mov_b64_e32 v[12:13], v[60:61]
	v_mov_b64_e32 v[14:15], v[62:63]
	v_mov_b64_e32 v[76:77], v[60:61]
	v_mov_b64_e32 v[74:75], v[58:59]
	v_mov_b64_e32 v[72:73], v[56:57]
	v_mov_b64_e32 v[70:71], v[54:55]
	v_mov_b64_e32 v[68:69], v[52:53]
	v_mov_b64_e32 v[66:67], v[50:51]
	v_mov_b64_e32 v[64:65], v[48:49]
	s_waitcnt lgkmcnt(0)
	s_barrier
	s_branch .LBB0_555
	s_nop 0
	s_nop 0
	s_nop 0
	s_nop 0
	s_nop 0
	s_nop 0

.LBB0_650:
	s_or_b64 exec, exec, s[8:9]
	s_mov_b64 s[8:9], exec
	v_mbcnt_lo_u32_b32 v0, s8, 0
	v_mbcnt_hi_u32_b32 v0, s9, v0
	v_cmp_eq_u32_e32 vcc, 0, v0
	s_waitcnt vmcnt(0)
	buffer_inv sc1
	s_and_saveexec_b64 s[14:15], vcc
	s_cbranch_execz .LBB0_652
	s_bcnt1_i32_b64 s3, s[8:9]
.LBB0_652:
	s_or_b64 exec, exec, s[14:15]
	s_waitcnt vmcnt(0)

.LBB0_766:
	s_or_b64 exec, exec, s[16:17]
	s_mov_b64 s[16:17], exec
	v_mbcnt_lo_u32_b32 v0, s16, 0
	v_mbcnt_hi_u32_b32 v0, s17, v0
	v_cmp_eq_u32_e32 vcc, 0, v0
	s_waitcnt vmcnt(0)
	buffer_inv sc1
	s_and_saveexec_b64 s[30:31], vcc
	s_cbranch_execz .LBB0_768
	s_bcnt1_i32_b64 s3, s[16:17]
.LBB0_768:
	s_or_b64 exec, exec, s[30:31]
	s_waitcnt vmcnt(0)

.LBB0_787:
	s_ashr_i32 s39, s38, 31
	s_lshl_b64 s[40:41], s[38:39], 20
	s_add_u32 s40, s12, s40
	s_addc_u32 s41, s13, s41
	s_and_b64 s[42:43], s[4:5], exec
	s_cselect_b32 s39, s41, s49
	s_cselect_b32 s45, s40, s48
	s_ashr_i32 s37, s36, 31
	s_lshl_b64 s[42:43], s[36:37], 20
	s_add_u32 s42, s28, s42
	s_addc_u32 s43, s29, s43
	s_and_b64 s[52:53], s[4:5], exec
	s_cselect_b32 s37, s43, s51
	s_cselect_b32 s66, s42, s50
	s_add_u32 s48, s48, 0x80080
	s_addc_u32 s49, s49, 0
	s_add_u32 s67, s50, 0x100
	v_mov_b32_e32 v0, 0
	s_addc_u32 s68, s51, 0
	s_mov_b32 s69, -2
	s_waitcnt lgkmcnt(0)
	v_mov_b32_e32 v1, v0
	v_mov_b32_e32 v2, v0
	v_mov_b32_e32 v3, v0
	v_mov_b32_e32 v4, v0
	v_mov_b32_e32 v5, v0
	v_mov_b32_e32 v6, v0
	v_mov_b32_e32 v7, v0
	v_mov_b32_e32 v16, v0
	v_mov_b32_e32 v17, v0
	v_mov_b32_e32 v18, v0
	v_mov_b32_e32 v19, v0
	v_mov_b32_e32 v20, v0
	v_mov_b32_e32 v21, v0
	v_mov_b32_e32 v22, v0
	v_mov_b32_e32 v23, v0
	v_mov_b32_e32 v32, v0
	v_mov_b32_e32 v33, v0
	v_mov_b32_e32 v34, v0
	v_mov_b32_e32 v35, v0
	v_mov_b32_e32 v36, v0
	v_mov_b32_e32 v37, v0
	v_mov_b32_e32 v38, v0
	v_mov_b32_e32 v39, v0
	v_mov_b32_e32 v48, v0
	v_mov_b32_e32 v49, v0
	v_mov_b32_e32 v50, v0
	v_mov_b32_e32 v51, v0
	v_mov_b32_e32 v52, v0
	v_mov_b32_e32 v53, v0
	v_mov_b32_e32 v54, v0
	v_mov_b32_e32 v55, v0
	v_mov_b32_e32 v8, v0
	v_mov_b32_e32 v9, v0
	v_mov_b32_e32 v10, v0
	v_mov_b32_e32 v11, v0
	v_mov_b32_e32 v12, v0
	v_mov_b32_e32 v13, v0
	v_mov_b32_e32 v14, v0
	v_mov_b32_e32 v15, v0
	v_mov_b32_e32 v24, v0
	v_mov_b32_e32 v25, v0
	v_mov_b32_e32 v26, v0
	v_mov_b32_e32 v27, v0
	v_mov_b32_e32 v28, v0
	v_mov_b32_e32 v29, v0
	v_mov_b32_e32 v30, v0
	v_mov_b32_e32 v31, v0
	v_mov_b32_e32 v40, v0
	v_mov_b32_e32 v41, v0
	v_mov_b32_e32 v42, v0
	v_mov_b32_e32 v43, v0
	v_mov_b32_e32 v44, v0
	v_mov_b32_e32 v45, v0
	v_mov_b32_e32 v46, v0
	v_mov_b32_e32 v47, v0
	v_mov_b32_e32 v56, v0
	v_mov_b32_e32 v57, v0
	v_mov_b32_e32 v58, v0
	v_mov_b32_e32 v59, v0
	v_mov_b32_e32 v60, v0
	v_mov_b32_e32 v61, v0
	v_mov_b32_e32 v62, v0
	v_mov_b32_e32 v63, v0
	v_mov_b32_e32 v64, v0
	v_mov_b32_e32 v65, v0
	v_mov_b32_e32 v66, v0
	v_mov_b32_e32 v67, v0
	v_mov_b32_e32 v68, v0
	v_mov_b32_e32 v69, v0
	v_mov_b32_e32 v70, v0
	v_mov_b32_e32 v71, v0
	v_mov_b32_e32 v80, v0
	v_mov_b32_e32 v81, v0
	v_mov_b32_e32 v82, v0
	v_mov_b32_e32 v83, v0
	v_mov_b32_e32 v84, v0
	v_mov_b32_e32 v85, v0
	v_mov_b32_e32 v86, v0
	v_mov_b32_e32 v87, v0
	v_mov_b32_e32 v96, v0
	v_mov_b32_e32 v97, v0
	v_mov_b32_e32 v98, v0
	v_mov_b32_e32 v99, v0
	v_mov_b32_e32 v100, v0
	v_mov_b32_e32 v101, v0
	v_mov_b32_e32 v102, v0
	v_mov_b32_e32 v103, v0
	v_mov_b32_e32 v112, v0
	v_mov_b32_e32 v113, v0
	v_mov_b32_e32 v114, v0
	v_mov_b32_e32 v115, v0
	v_mov_b32_e32 v116, v0
	v_mov_b32_e32 v117, v0
	v_mov_b32_e32 v118, v0
	v_mov_b32_e32 v119, v0
	v_mov_b32_e32 v72, v0
	v_mov_b32_e32 v73, v0
	v_mov_b32_e32 v74, v0
	v_mov_b32_e32 v75, v0
	v_mov_b32_e32 v76, v0
	v_mov_b32_e32 v77, v0
	v_mov_b32_e32 v78, v0
	v_mov_b32_e32 v79, v0
	v_mov_b32_e32 v88, v0
	v_mov_b32_e32 v89, v0
	v_mov_b32_e32 v90, v0
	v_mov_b32_e32 v91, v0
	v_mov_b32_e32 v92, v0
	v_mov_b32_e32 v93, v0
	v_mov_b32_e32 v94, v0
	v_mov_b32_e32 v95, v0
	v_mov_b32_e32 v104, v0
	v_mov_b32_e32 v105, v0
	v_mov_b32_e32 v106, v0
	v_mov_b32_e32 v107, v0
	v_mov_b32_e32 v108, v0
	v_mov_b32_e32 v109, v0
	v_mov_b32_e32 v110, v0
	v_mov_b32_e32 v111, v0
	v_mov_b32_e32 v120, v0
	v_mov_b32_e32 v121, v0
	v_mov_b32_e32 v122, v0
	v_mov_b32_e32 v123, v0
	v_mov_b32_e32 v124, v0
	v_mov_b32_e32 v125, v0
	v_mov_b32_e32 v126, v0
	v_mov_b32_e32 v127, v0
	s_nop 0
.LBB0_788:
	ds_read_b128 v[144:147], v157
	ds_read_b128 v[148:151], v157 offset:1024
	ds_read_b128 v[162:165], v157 offset:2048
	ds_read_b128 v[166:169], v157 offset:3072
	ds_read_b128 v[170:173], v158
	ds_read_b128 v[174:177], v158 offset:1024
	ds_read_b128 v[178:181], v158 offset:2048
	ds_read_b128 v[182:185], v158 offset:3072
	s_add_u32 s50, s48, 0xfff80080
	s_addc_u32 s51, s49, -1
	s_cmp_eq_u32 s69, 28
	s_cselect_b32 s53, s39, s51
	s_cselect_b32 s52, s45, s50
	s_cselect_b32 s51, s37, s68
	s_cselect_b32 s50, s66, s67
	v_lshl_add_u64 v[152:153], s[48:49], 0, v[136:137]
	s_add_i32 m0, s47, 0xc000
	ds_read_b128 v[186:189], v159
	ds_read_b128 v[190:193], v159 offset:1024
	ds_read_b128 v[194:197], v159 offset:2048
	ds_read_b128 v[198:201], v159 offset:3072
	ds_read_b128 v[202:205], v159 offset:4096
	ds_read_b128 v[206:209], v159 offset:5120
	ds_read_b128 v[210:213], v159 offset:6144
	ds_read_b128 v[214:217], v159 offset:7168
	global_load_lds_dwordx4 v[152:153], off
	v_lshl_add_u64 v[152:153], s[48:49], 0, v[138:139]
	s_add_i32 m0, s47, 0xe000
	s_nop 0
	global_load_lds_dwordx4 v[152:153], off
	s_waitcnt vmcnt(8)
	s_waitcnt lgkmcnt(0)
	s_barrier
	s_setprio 1
	s_waitcnt lgkmcnt(0)
	v_mfma_f32_16x16x32_bf16 v[124:127], v[144:147], v[186:189], v[124:127]
	v_mfma_f32_16x16x32_bf16 v[120:123], v[162:165], v[186:189], v[120:123]
	v_mfma_f32_16x16x32_bf16 v[108:111], v[144:147], v[194:197], v[108:111]
	v_mfma_f32_16x16x32_bf16 v[104:107], v[162:165], v[194:197], v[104:107]
	v_mfma_f32_16x16x32_bf16 v[92:95], v[144:147], v[202:205], v[92:95]
	v_mfma_f32_16x16x32_bf16 v[88:91], v[162:165], v[202:205], v[88:91]
	v_mfma_f32_16x16x32_bf16 v[76:79], v[144:147], v[210:213], v[76:79]
	v_mfma_f32_16x16x32_bf16 v[72:75], v[162:165], v[210:213], v[72:75]
	v_mfma_f32_16x16x32_bf16 v[124:127], v[148:151], v[190:193], v[124:127]
	v_mfma_f32_16x16x32_bf16 v[120:123], v[166:169], v[190:193], v[120:123]
	v_mfma_f32_16x16x32_bf16 v[108:111], v[148:151], v[198:201], v[108:111]
	v_mfma_f32_16x16x32_bf16 v[104:107], v[166:169], v[198:201], v[104:107]
	v_mfma_f32_16x16x32_bf16 v[92:95], v[148:151], v[206:209], v[92:95]
	v_mfma_f32_16x16x32_bf16 v[88:91], v[166:169], v[206:209], v[88:91]
	v_mfma_f32_16x16x32_bf16 v[76:79], v[148:151], v[214:217], v[76:79]
	v_mfma_f32_16x16x32_bf16 v[72:75], v[166:169], v[214:217], v[72:75]
	s_setprio 0
	s_setprio 1
	v_mfma_f32_16x16x32_bf16 v[116:119], v[170:173], v[186:189], v[116:119]
	v_mfma_f32_16x16x32_bf16 v[112:115], v[178:181], v[186:189], v[112:115]
	v_mfma_f32_16x16x32_bf16 v[100:103], v[170:173], v[194:197], v[100:103]
	v_mfma_f32_16x16x32_bf16 v[96:99], v[178:181], v[194:197], v[96:99]
	v_mfma_f32_16x16x32_bf16 v[84:87], v[170:173], v[202:205], v[84:87]
	v_mfma_f32_16x16x32_bf16 v[80:83], v[178:181], v[202:205], v[80:83]
	v_mfma_f32_16x16x32_bf16 v[68:71], v[170:173], v[210:213], v[68:71]
	v_mfma_f32_16x16x32_bf16 v[64:67], v[178:181], v[210:213], v[64:67]
	v_mfma_f32_16x16x32_bf16 v[116:119], v[174:177], v[190:193], v[116:119]
	v_mfma_f32_16x16x32_bf16 v[112:115], v[182:185], v[190:193], v[112:115]
	v_mfma_f32_16x16x32_bf16 v[100:103], v[174:177], v[198:201], v[100:103]
	v_mfma_f32_16x16x32_bf16 v[96:99], v[182:185], v[198:201], v[96:99]
	v_mfma_f32_16x16x32_bf16 v[84:87], v[174:177], v[206:209], v[84:87]
	v_mfma_f32_16x16x32_bf16 v[80:83], v[182:185], v[206:209], v[80:83]
	v_mfma_f32_16x16x32_bf16 v[68:71], v[174:177], v[214:217], v[68:71]
	v_mfma_f32_16x16x32_bf16 v[64:67], v[182:185], v[214:217], v[64:67]
	s_setprio 0
	s_barrier
	s_add_i32 s70, s63, s3
	v_lshl_add_u64 v[152:153], s[50:51], 0, v[130:131]
	s_mov_b32 m0, s70
	ds_read_b128 v[186:189], v159 offset:16384
	ds_read_b128 v[190:193], v159 offset:17408
	ds_read_b128 v[194:197], v159 offset:18432
	ds_read_b128 v[198:201], v159 offset:19456
	ds_read_b128 v[202:205], v159 offset:20480
	ds_read_b128 v[206:209], v159 offset:21504
	ds_read_b128 v[210:213], v159 offset:22528
	ds_read_b128 v[214:217], v159 offset:23552
	global_load_lds_dwordx4 v[152:153], off
	s_add_i32 m0, s70, 0x2000
	s_add_u32 s70, s50, 0x80000
	v_lshl_add_u64 v[218:219], s[50:51], 0, v[134:135]
	s_addc_u32 s71, s51, 0
	s_add_i32 s72, s64, s3
	global_load_lds_dwordx4 v[218:219], off
	v_lshl_add_u64 v[220:221], s[70:71], 0, v[130:131]
	s_mov_b32 m0, s72
	v_lshl_add_u64 v[222:223], s[52:53], 0, v[132:133]
	global_load_lds_dwordx4 v[220:221], off
	v_lshl_add_u64 v[220:221], s[70:71], 0, v[134:135]
	s_add_i32 m0, s72, 0x2000
	s_nop 0
	global_load_lds_dwordx4 v[220:221], off
	v_lshl_add_u64 v[220:221], s[52:53], 0, v[128:129]
	s_mov_b32 m0, s47
	s_nop 0
	global_load_lds_dwordx4 v[220:221], off
	s_mov_b32 m0, s54
	s_nop 0
	global_load_lds_dwordx4 v[222:223], off
	s_waitcnt vmcnt(8)
	s_waitcnt lgkmcnt(0)
	s_barrier
	s_setprio 1
	s_waitcnt lgkmcnt(0)
	v_mfma_f32_16x16x32_bf16 v[60:63], v[144:147], v[186:189], v[60:63]
	v_mfma_f32_16x16x32_bf16 v[56:59], v[162:165], v[186:189], v[56:59]
	v_mfma_f32_16x16x32_bf16 v[44:47], v[144:147], v[194:197], v[44:47]
	v_mfma_f32_16x16x32_bf16 v[40:43], v[162:165], v[194:197], v[40:43]
	v_mfma_f32_16x16x32_bf16 v[28:31], v[144:147], v[202:205], v[28:31]
	v_mfma_f32_16x16x32_bf16 v[24:27], v[162:165], v[202:205], v[24:27]
	v_mfma_f32_16x16x32_bf16 v[12:15], v[144:147], v[210:213], v[12:15]
	v_mfma_f32_16x16x32_bf16 v[8:11], v[162:165], v[210:213], v[8:11]
	v_mfma_f32_16x16x32_bf16 v[60:63], v[148:151], v[190:193], v[60:63]
	v_mfma_f32_16x16x32_bf16 v[56:59], v[166:169], v[190:193], v[56:59]
	v_mfma_f32_16x16x32_bf16 v[44:47], v[148:151], v[198:201], v[44:47]
	v_mfma_f32_16x16x32_bf16 v[40:43], v[166:169], v[198:201], v[40:43]
	v_mfma_f32_16x16x32_bf16 v[28:31], v[148:151], v[206:209], v[28:31]
	v_mfma_f32_16x16x32_bf16 v[24:27], v[166:169], v[206:209], v[24:27]
	v_mfma_f32_16x16x32_bf16 v[12:15], v[148:151], v[214:217], v[12:15]
	v_mfma_f32_16x16x32_bf16 v[8:11], v[166:169], v[214:217], v[8:11]
	s_setprio 0
	s_setprio 1
	v_mfma_f32_16x16x32_bf16 v[52:55], v[170:173], v[186:189], v[52:55]
	v_mfma_f32_16x16x32_bf16 v[48:51], v[178:181], v[186:189], v[48:51]
	v_mfma_f32_16x16x32_bf16 v[36:39], v[170:173], v[194:197], v[36:39]
	v_mfma_f32_16x16x32_bf16 v[32:35], v[178:181], v[194:197], v[32:35]
	v_mfma_f32_16x16x32_bf16 v[20:23], v[170:173], v[202:205], v[20:23]
	v_mfma_f32_16x16x32_bf16 v[16:19], v[178:181], v[202:205], v[16:19]
	v_mfma_f32_16x16x32_bf16 v[4:7], v[170:173], v[210:213], v[4:7]
	v_mfma_f32_16x16x32_bf16 v[0:3], v[178:181], v[210:213], v[0:3]
	v_mfma_f32_16x16x32_bf16 v[52:55], v[174:177], v[190:193], v[52:55]
	v_mfma_f32_16x16x32_bf16 v[48:51], v[182:185], v[190:193], v[48:51]
	v_mfma_f32_16x16x32_bf16 v[36:39], v[174:177], v[198:201], v[36:39]
	v_mfma_f32_16x16x32_bf16 v[32:35], v[182:185], v[198:201], v[32:35]
	v_mfma_f32_16x16x32_bf16 v[20:23], v[174:177], v[206:209], v[20:23]
	v_mfma_f32_16x16x32_bf16 v[16:19], v[182:185], v[206:209], v[16:19]
	v_mfma_f32_16x16x32_bf16 v[4:7], v[174:177], v[214:217], v[4:7]
	v_mfma_f32_16x16x32_bf16 v[0:3], v[182:185], v[214:217], v[0:3]
	s_setprio 0
	s_barrier
	s_add_i32 s70, 0, 0x18000
	s_add_i32 s71, 0, 0x1c000
	v_add_u32_e32 v166, s70, v155
	v_add_u32_e32 v182, s71, v155
	ds_read_b128 v[144:147], v166
	ds_read_b128 v[148:151], v166 offset:1024
	ds_read_b128 v[162:165], v166 offset:2048
	ds_read_b128 v[166:169], v166 offset:3072
	ds_read_b128 v[170:173], v182
	ds_read_b128 v[174:177], v182 offset:1024
	ds_read_b128 v[178:181], v182 offset:2048
	ds_read_b128 v[182:185], v182 offset:3072
	s_add_u32 s52, s52, 0x80000
	s_addc_u32 s53, s53, 0
	s_mov_b32 m0, s55
	v_lshl_add_u64 v[226:227], s[52:53], 0, v[128:129]
	ds_read_b128 v[186:189], v159 offset:32768
	ds_read_b128 v[190:193], v159 offset:33792
	ds_read_b128 v[194:197], v159 offset:34816
	ds_read_b128 v[198:201], v159 offset:35840
	ds_read_b128 v[202:205], v159 offset:36864
	ds_read_b128 v[206:209], v159 offset:37888
	ds_read_b128 v[210:213], v159 offset:38912
	ds_read_b128 v[214:217], v159 offset:39936
	global_load_lds_dwordx4 v[226:227], off
	v_lshl_add_u64 v[226:227], s[52:53], 0, v[132:133]
	s_mov_b32 m0, s56
	s_nop 0
	global_load_lds_dwordx4 v[226:227], off
	s_waitcnt vmcnt(8)
	s_waitcnt lgkmcnt(0)
	s_barrier
	s_setprio 1
	s_waitcnt lgkmcnt(0)
	v_mfma_f32_16x16x32_bf16 v[124:127], v[144:147], v[186:189], v[124:127]
	v_mfma_f32_16x16x32_bf16 v[120:123], v[162:165], v[186:189], v[120:123]
	v_mfma_f32_16x16x32_bf16 v[108:111], v[144:147], v[194:197], v[108:111]
	v_mfma_f32_16x16x32_bf16 v[104:107], v[162:165], v[194:197], v[104:107]
	v_mfma_f32_16x16x32_bf16 v[92:95], v[144:147], v[202:205], v[92:95]
	v_mfma_f32_16x16x32_bf16 v[88:91], v[162:165], v[202:205], v[88:91]
	v_mfma_f32_16x16x32_bf16 v[76:79], v[144:147], v[210:213], v[76:79]
	v_mfma_f32_16x16x32_bf16 v[72:75], v[162:165], v[210:213], v[72:75]
	v_mfma_f32_16x16x32_bf16 v[124:127], v[148:151], v[190:193], v[124:127]
	v_mfma_f32_16x16x32_bf16 v[120:123], v[166:169], v[190:193], v[120:123]
	v_mfma_f32_16x16x32_bf16 v[108:111], v[148:151], v[198:201], v[108:111]
	v_mfma_f32_16x16x32_bf16 v[104:107], v[166:169], v[198:201], v[104:107]
	v_mfma_f32_16x16x32_bf16 v[92:95], v[148:151], v[206:209], v[92:95]
	v_mfma_f32_16x16x32_bf16 v[88:91], v[166:169], v[206:209], v[88:91]
	v_mfma_f32_16x16x32_bf16 v[76:79], v[148:151], v[214:217], v[76:79]
	v_mfma_f32_16x16x32_bf16 v[72:75], v[166:169], v[214:217], v[72:75]
	s_setprio 0
	s_setprio 1
	v_mfma_f32_16x16x32_bf16 v[116:119], v[170:173], v[186:189], v[116:119]
	v_mfma_f32_16x16x32_bf16 v[112:115], v[178:181], v[186:189], v[112:115]
	v_mfma_f32_16x16x32_bf16 v[100:103], v[170:173], v[194:197], v[100:103]
	v_mfma_f32_16x16x32_bf16 v[96:99], v[178:181], v[194:197], v[96:99]
	v_mfma_f32_16x16x32_bf16 v[84:87], v[170:173], v[202:205], v[84:87]
	v_mfma_f32_16x16x32_bf16 v[80:83], v[178:181], v[202:205], v[80:83]
	v_mfma_f32_16x16x32_bf16 v[68:71], v[170:173], v[210:213], v[68:71]
	v_mfma_f32_16x16x32_bf16 v[64:67], v[178:181], v[210:213], v[64:67]
	v_mfma_f32_16x16x32_bf16 v[116:119], v[174:177], v[190:193], v[116:119]
	v_mfma_f32_16x16x32_bf16 v[112:115], v[182:185], v[190:193], v[112:115]
	v_mfma_f32_16x16x32_bf16 v[100:103], v[174:177], v[198:201], v[100:103]
	v_mfma_f32_16x16x32_bf16 v[96:99], v[182:185], v[198:201], v[96:99]
	v_mfma_f32_16x16x32_bf16 v[84:87], v[174:177], v[206:209], v[84:87]
	v_mfma_f32_16x16x32_bf16 v[80:83], v[182:185], v[206:209], v[80:83]
	v_mfma_f32_16x16x32_bf16 v[68:71], v[174:177], v[214:217], v[68:71]
	v_mfma_f32_16x16x32_bf16 v[64:67], v[182:185], v[214:217], v[64:67]
	s_setprio 0
	s_barrier
	s_add_i32 s52, s70, s3
	v_lshl_add_u64 v[152:153], v[152:153], 0, s[30:31]
	s_mov_b32 m0, s52
	ds_read_b128 v[186:189], v159 offset:49152
	ds_read_b128 v[190:193], v159 offset:50176
	ds_read_b128 v[194:197], v159 offset:51200
	ds_read_b128 v[198:201], v159 offset:52224
	ds_read_b128 v[202:205], v159 offset:53248
	ds_read_b128 v[206:209], v159 offset:54272
	ds_read_b128 v[210:213], v159 offset:55296
	ds_read_b128 v[214:217], v159 offset:56320
	global_load_lds_dwordx4 v[152:153], off
	s_add_i32 m0, s52, 0x2000
	s_add_u32 s50, s50, 0x80080
	v_lshl_add_u64 v[152:153], v[218:219], 0, s[30:31]
	s_addc_u32 s51, s51, 0
	s_add_i32 s52, s71, s3
	global_load_lds_dwordx4 v[152:153], off
	v_lshl_add_u64 v[152:153], s[50:51], 0, v[130:131]
	s_mov_b32 m0, s52
	s_nop 0
	global_load_lds_dwordx4 v[152:153], off
	v_lshl_add_u64 v[152:153], s[50:51], 0, v[134:135]
	s_add_i32 m0, s52, 0x2000
	s_nop 0
	global_load_lds_dwordx4 v[152:153], off
	v_lshl_add_u64 v[152:153], v[220:221], 0, s[30:31]
	s_mov_b32 m0, s58
	s_nop 0
	global_load_lds_dwordx4 v[152:153], off
	v_lshl_add_u64 v[152:153], v[222:223], 0, s[30:31]
	s_mov_b32 m0, s59
	s_nop 0
	global_load_lds_dwordx4 v[152:153], off
	s_waitcnt vmcnt(8)
	s_waitcnt lgkmcnt(0)
	s_barrier
	s_setprio 1
	s_waitcnt lgkmcnt(0)
	v_mfma_f32_16x16x32_bf16 v[60:63], v[144:147], v[186:189], v[60:63]
	v_mfma_f32_16x16x32_bf16 v[56:59], v[162:165], v[186:189], v[56:59]
	v_mfma_f32_16x16x32_bf16 v[44:47], v[144:147], v[194:197], v[44:47]
	v_mfma_f32_16x16x32_bf16 v[40:43], v[162:165], v[194:197], v[40:43]
	v_mfma_f32_16x16x32_bf16 v[28:31], v[144:147], v[202:205], v[28:31]
	v_mfma_f32_16x16x32_bf16 v[24:27], v[162:165], v[202:205], v[24:27]
	v_mfma_f32_16x16x32_bf16 v[12:15], v[144:147], v[210:213], v[12:15]
	v_mfma_f32_16x16x32_bf16 v[8:11], v[162:165], v[210:213], v[8:11]
	v_mfma_f32_16x16x32_bf16 v[60:63], v[148:151], v[190:193], v[60:63]
	v_mfma_f32_16x16x32_bf16 v[56:59], v[166:169], v[190:193], v[56:59]
	v_mfma_f32_16x16x32_bf16 v[44:47], v[148:151], v[198:201], v[44:47]
	v_mfma_f32_16x16x32_bf16 v[40:43], v[166:169], v[198:201], v[40:43]
	v_mfma_f32_16x16x32_bf16 v[28:31], v[148:151], v[206:209], v[28:31]
	v_mfma_f32_16x16x32_bf16 v[24:27], v[166:169], v[206:209], v[24:27]
	v_mfma_f32_16x16x32_bf16 v[12:15], v[148:151], v[214:217], v[12:15]
	v_mfma_f32_16x16x32_bf16 v[8:11], v[166:169], v[214:217], v[8:11]
	s_setprio 0
	s_setprio 1
	v_mfma_f32_16x16x32_bf16 v[52:55], v[170:173], v[186:189], v[52:55]
	v_mfma_f32_16x16x32_bf16 v[48:51], v[178:181], v[186:189], v[48:51]
	v_mfma_f32_16x16x32_bf16 v[36:39], v[170:173], v[194:197], v[36:39]
	v_mfma_f32_16x16x32_bf16 v[32:35], v[178:181], v[194:197], v[32:35]
	v_mfma_f32_16x16x32_bf16 v[20:23], v[170:173], v[202:205], v[20:23]
	v_mfma_f32_16x16x32_bf16 v[16:19], v[178:181], v[202:205], v[16:19]
	v_mfma_f32_16x16x32_bf16 v[4:7], v[170:173], v[210:213], v[4:7]
	v_mfma_f32_16x16x32_bf16 v[0:3], v[178:181], v[210:213], v[0:3]
	v_mfma_f32_16x16x32_bf16 v[52:55], v[174:177], v[190:193], v[52:55]
	v_mfma_f32_16x16x32_bf16 v[48:51], v[182:185], v[190:193], v[48:51]
	v_mfma_f32_16x16x32_bf16 v[36:39], v[174:177], v[198:201], v[36:39]
	v_mfma_f32_16x16x32_bf16 v[32:35], v[182:185], v[198:201], v[32:35]
	v_mfma_f32_16x16x32_bf16 v[20:23], v[174:177], v[206:209], v[20:23]
	v_mfma_f32_16x16x32_bf16 v[16:19], v[182:185], v[206:209], v[16:19]
	v_mfma_f32_16x16x32_bf16 v[4:7], v[174:177], v[214:217], v[4:7]
	v_mfma_f32_16x16x32_bf16 v[0:3], v[182:185], v[214:217], v[0:3]
	s_setprio 0
	s_barrier
	s_add_i32 s69, s69, 2
	s_add_u32 s48, s48, 0x100
	s_addc_u32 s49, s49, 0
	s_add_u32 s67, s67, 0x100
	s_addc_u32 s68, s68, 0
	s_cmp_gt_u32 s69, 29
	s_cbranch_scc0 .LBB0_788
	s_and_b64 vcc, exec, s[34:35]
	s_cbranch_vccz .LBB0_791
	s_barrier

.LBB0_860:
	s_or_b64 exec, exec, s[4:5]
	s_mov_b64 s[4:5], exec
	v_mbcnt_lo_u32_b32 v0, s4, 0
	v_mbcnt_hi_u32_b32 v0, s5, v0
	v_cmp_eq_u32_e32 vcc, 0, v0
	s_waitcnt vmcnt(0)
	buffer_inv sc1
	s_and_saveexec_b64 s[6:7], vcc
	s_cbranch_execz .LBB0_862
	s_bcnt1_i32_b64 s4, s[4:5]
.LBB0_862:
	s_or_b64 exec, exec, s[6:7]
	s_waitcnt vmcnt(0)
